# P1 in-proj epilogue stores (Q/K/V/UB) made write-through (sc1): less dirty L2 data for the P1|P2 seam to write back
# speedup vs baseline: 1.0112x; 1.0112x over previous
; __device__ __forceinline__ u32x4 pack8(f32x4 v0, f32x4 v1) { u32x4 w; w.x = pk2(v0[0], v0[1]); w.y = pk2(v0[2], v0[3]); w.z = pk2(v1[0], v1[1]); w.w = pk2(v1[2], v1[3]); return w; }
;     __device__ __forceinline__ void operator()(const f32x4 (&acc)[2][2][4][2], const Unit& u, int wr, int wc, int fr, int fq) const {
;     ...
;                 const int row = row0 + ai * 128 + m * 16; const float rs = rt[ai * 128 + wr * 64 + m * 16 + fr];
; #pragma unroll
;                 for (int bj = 0; bj < 2; ++bj) {
;                     const int cb = bj * 128 + wc * 32 + 8 * fq;
;                     const u32x4 w = pack8(acc[ai][bj][m][0] * rs, acc[ai][bj][m][1] * rs);
;                     bf16_t* dst;
;                     if (u.pn < 2) dst = Q + (size_t)row * 512 + u.pn * 256 + cb;
;                     else if (u.pn == 2) dst = (bj == 0 ? K : V) + (size_t)row * 128 + wc * 32 + 8 * fq;
;                     else { const int j = (u.pn - 3) * 256 + cb, g = j >> 4, h = j & 15; dst = UB + ((size_t)(g * NCH + (row >> 5)) * UK + (row & 31) * 16 + h); }
;                     *(u32x4*)dst = w;
.LBB0_183:
	s_waitcnt lgkmcnt(0)
	v_pk_mul_f32 v[126:127], v[126:127], v[152:153] op_sel_hi:[1,0]
	v_pk_mul_f32 v[124:125], v[124:125], v[152:153] op_sel_hi:[1,0]
	v_pk_mul_f32 v[164:165], v[122:123], v[152:153] op_sel_hi:[1,0]
	v_pk_mul_f32 v[122:123], v[120:121], v[152:153] op_sel_hi:[1,0]
	v_cvt_pk_bf16_f32 v120, v124, v125
	v_cvt_pk_bf16_f32 v121, v126, v127
	v_cvt_pk_bf16_f32 v122, v122, v123
	v_cvt_pk_bf16_f32 v123, v164, v165
	flat_store_dwordx4 v[158:159], v[120:123] sc1
	s_mov_b64 s[52:53], -1
	s_andn2_b64 vcc, exec, s[28:29]
	v_cndmask_b32_e64 v120, 0, 1, s[28:29]
	v_cmp_ne_u32_e64 s[42:43], 1, v120
	v_cndmask_b32_e64 v120, 0, 1, s[30:31]
	v_cmp_ne_u32_e64 s[40:41], 1, v120
	s_cbranch_vccnz .LBB0_189
	s_and_b64 vcc, exec, s[40:41]
	s_mov_b64 s[28:29], -1
	s_cbranch_vccnz .LBB0_186
	v_or_b32_e32 v120, s11, v160
	v_lshlrev_b32_e32 v120, 5, v120
	v_and_b32_e32 v120, 0x7ffffe00, v120
	v_add_u32_e32 v120, s13, v120
	v_mad_i64_i32 v[120:121], s[28:29], v120, s60, v[140:141]
	s_mov_b64 s[28:29], 0

; __device__ __forceinline__ u32x4 pack8(f32x4 v0, f32x4 v1) { u32x4 w; w.x = pk2(v0[0], v0[1]); w.y = pk2(v0[2], v0[3]); w.z = pk2(v1[0], v1[1]); w.w = pk2(v1[2], v1[3]); return w; }
;     __device__ __forceinline__ void operator()(const f32x4 (&acc)[2][2][4][2], const Unit& u, int wr, int wc, int fr, int fq) const {
;     ...
;                 const int row = row0 + ai * 128 + m * 16; const float rs = rt[ai * 128 + wr * 64 + m * 16 + fr];
; #pragma unroll
;                 for (int bj = 0; bj < 2; ++bj) {
;                     const int cb = bj * 128 + wc * 32 + 8 * fq;
;                     const u32x4 w = pack8(acc[ai][bj][m][0] * rs, acc[ai][bj][m][1] * rs);
;                     bf16_t* dst;
;                     if (u.pn < 2) dst = Q + (size_t)row * 512 + u.pn * 256 + cb;
;                     else if (u.pn == 2) dst = (bj == 0 ? K : V) + (size_t)row * 128 + wc * 32 + 8 * fq;
;                     else { const int j = (u.pn - 3) * 256 + cb, g = j >> 4, h = j & 15; dst = UB + ((size_t)(g * NCH + (row >> 5)) * UK + (row & 31) * 16 + h); }
;                     *(u32x4*)dst = w;
.LBB0_191:
	v_mov_b32_e32 v153, v152
	v_mov_b32_e32 v122, v152
	v_mov_b32_e32 v123, v152
	v_pk_mul_f32 v[118:119], v[118:119], v[122:123]
	v_pk_mul_f32 v[116:117], v[116:117], v[152:153]
	v_pk_mul_f32 v[122:123], v[114:115], v[122:123]
	v_pk_mul_f32 v[114:115], v[112:113], v[152:153]
	v_cvt_pk_bf16_f32 v112, v116, v117
	v_cvt_pk_bf16_f32 v113, v118, v119
	v_cvt_pk_bf16_f32 v114, v114, v115
	v_cvt_pk_bf16_f32 v115, v122, v123
	flat_store_dwordx4 v[120:121], v[112:115] sc1
	ds_read_b32 v112, v163 offset:64
	v_or_b32_e32 v116, 16, v150
	v_lshlrev_b32_e32 v113, 4, v116
	v_ashrrev_i32_e32 v117, 31, v116
	v_and_b32_e32 v113, 0x1f0, v113
	v_lshlrev_b64 v[114:115], 8, v[116:117]
	s_and_b64 vcc, exec, s[42:43]
	s_mov_b64 s[28:29], -1
	s_cbranch_vccnz .LBB0_197
	s_and_b64 vcc, exec, s[40:41]
	s_cbranch_vccnz .LBB0_194
	v_or_b32_e32 v118, s11, v138
	v_lshlrev_b32_e32 v118, 5, v118
	v_and_b32_e32 v118, 0x7fffee00, v118
	v_add_u32_e32 v120, s13, v118
	v_mov_b64_e32 v[118:119], s[44:45]
	v_mad_i64_i32 v[118:119], s[28:29], v120, s60, v[118:119]
	v_lshlrev_b32_e32 v120, 1, v113
	v_mov_b32_e32 v121, v201
	v_lshl_add_u64 v[118:119], v[118:119], 0, v[120:121]
	v_lshlrev_b32_e32 v120, 1, v136
	v_lshl_add_u64 v[118:119], v[118:119], 0, v[120:121]
	s_mov_b64 s[28:29], 0

; __device__ __forceinline__ u32x4 pack8(f32x4 v0, f32x4 v1) { u32x4 w; w.x = pk2(v0[0], v0[1]); w.y = pk2(v0[2], v0[3]); w.z = pk2(v1[0], v1[1]); w.w = pk2(v1[2], v1[3]); return w; }
;     __device__ __forceinline__ void operator()(const f32x4 (&acc)[2][2][4][2], const Unit& u, int wr, int wc, int fr, int fq) const {
;     ...
;                 const int row = row0 + ai * 128 + m * 16; const float rs = rt[ai * 128 + wr * 64 + m * 16 + fr];
; #pragma unroll
;                 for (int bj = 0; bj < 2; ++bj) {
;                     const int cb = bj * 128 + wc * 32 + 8 * fq;
;                     const u32x4 w = pack8(acc[ai][bj][m][0] * rs, acc[ai][bj][m][1] * rs);
;                     bf16_t* dst;
;                     if (u.pn < 2) dst = Q + (size_t)row * 512 + u.pn * 256 + cb;
;                     else if (u.pn == 2) dst = (bj == 0 ? K : V) + (size_t)row * 128 + wc * 32 + 8 * fq;
;                     else { const int j = (u.pn - 3) * 256 + cb, g = j >> 4, h = j & 15; dst = UB + ((size_t)(g * NCH + (row >> 5)) * UK + (row & 31) * 16 + h); }
;                     *(u32x4*)dst = w;
.LBB0_199:
	s_waitcnt lgkmcnt(0)
	v_pk_mul_f32 v[110:111], v[110:111], v[112:113] op_sel_hi:[1,0]
	v_pk_mul_f32 v[108:109], v[108:109], v[112:113] op_sel_hi:[1,0]
	v_pk_mul_f32 v[120:121], v[106:107], v[112:113] op_sel_hi:[1,0]
	v_pk_mul_f32 v[106:107], v[104:105], v[112:113] op_sel_hi:[1,0]
	v_cvt_pk_bf16_f32 v104, v108, v109
	v_cvt_pk_bf16_f32 v105, v110, v111
	v_cvt_pk_bf16_f32 v106, v106, v107
	v_cvt_pk_bf16_f32 v107, v120, v121
	s_and_b64 vcc, exec, s[42:43]
	s_mov_b64 s[28:29], -1
	flat_store_dwordx4 v[118:119], v[104:107] sc1
	s_cbranch_vccnz .LBB0_205
	s_and_b64 vcc, exec, s[40:41]
	s_cbranch_vccnz .LBB0_202
	v_or_b32_e32 v104, s11, v160
	v_lshlrev_b32_e32 v104, 5, v104
	v_and_b32_e32 v104, 0x7ffffe00, v104
	v_add_u32_e32 v106, s13, v104
	v_mov_b64_e32 v[104:105], s[44:45]
	v_mad_i64_i32 v[104:105], s[28:29], v106, s60, v[104:105]
	v_lshlrev_b32_e32 v106, 1, v113
	v_mov_b32_e32 v107, v201
	v_lshl_add_u64 v[104:105], v[104:105], 0, v[106:107]
	v_lshlrev_b32_e32 v106, 1, v136
	v_lshl_add_u64 v[104:105], v[104:105], 0, v[106:107]
	s_mov_b64 s[28:29], 0

; __device__ __forceinline__ u32x4 pack8(f32x4 v0, f32x4 v1) { u32x4 w; w.x = pk2(v0[0], v0[1]); w.y = pk2(v0[2], v0[3]); w.z = pk2(v1[0], v1[1]); w.w = pk2(v1[2], v1[3]); return w; }
;     __device__ __forceinline__ void operator()(const f32x4 (&acc)[2][2][4][2], const Unit& u, int wr, int wc, int fr, int fq) const {
;     ...
;                 const int row = row0 + ai * 128 + m * 16; const float rs = rt[ai * 128 + wr * 64 + m * 16 + fr];
; #pragma unroll
;                 for (int bj = 0; bj < 2; ++bj) {
;                     const int cb = bj * 128 + wc * 32 + 8 * fq;
;                     const u32x4 w = pack8(acc[ai][bj][m][0] * rs, acc[ai][bj][m][1] * rs);
;                     bf16_t* dst;
;                     if (u.pn < 2) dst = Q + (size_t)row * 512 + u.pn * 256 + cb;
;                     else if (u.pn == 2) dst = (bj == 0 ? K : V) + (size_t)row * 128 + wc * 32 + 8 * fq;
;                     else { const int j = (u.pn - 3) * 256 + cb, g = j >> 4, h = j & 15; dst = UB + ((size_t)(g * NCH + (row >> 5)) * UK + (row & 31) * 16 + h); }
;                     *(u32x4*)dst = w;
.LBB0_207:
	v_mov_b32_e32 v113, v112
	v_mov_b32_e32 v106, v112
	v_mov_b32_e32 v107, v112
	v_pk_mul_f32 v[102:103], v[102:103], v[106:107]
	v_pk_mul_f32 v[100:101], v[100:101], v[112:113]
	v_pk_mul_f32 v[106:107], v[98:99], v[106:107]
	v_pk_mul_f32 v[98:99], v[96:97], v[112:113]
	v_cvt_pk_bf16_f32 v96, v100, v101
	v_cvt_pk_bf16_f32 v97, v102, v103
	v_cvt_pk_bf16_f32 v98, v98, v99
	v_cvt_pk_bf16_f32 v99, v106, v107
	flat_store_dwordx4 v[104:105], v[96:99] sc1
	ds_read_b32 v96, v163 offset:128
	v_or_b32_e32 v100, 32, v150
	v_ashrrev_i32_e32 v101, 31, v100
	v_ashrrev_i32_e32 v97, 5, v100
	v_lshlrev_b64 v[98:99], 8, v[100:101]
	s_and_b64 vcc, exec, s[42:43]
	s_mov_b64 s[28:29], -1
	s_cbranch_vccnz .LBB0_213
	s_and_b64 vcc, exec, s[40:41]
	s_cbranch_vccnz .LBB0_210
	v_or_b32_e32 v102, s11, v138
	v_lshlrev_b32_e32 v102, 5, v102
	v_and_b32_e32 v102, 0x7fffee00, v102
	v_add_u32_e32 v102, v97, v102
	v_mad_i64_i32 v[102:103], s[28:29], v102, s60, v[140:141]
	s_mov_b64 s[28:29], 0

; __device__ __forceinline__ u32x4 pack8(f32x4 v0, f32x4 v1) { u32x4 w; w.x = pk2(v0[0], v0[1]); w.y = pk2(v0[2], v0[3]); w.z = pk2(v1[0], v1[1]); w.w = pk2(v1[2], v1[3]); return w; }
;     __device__ __forceinline__ void operator()(const f32x4 (&acc)[2][2][4][2], const Unit& u, int wr, int wc, int fr, int fq) const {
;     ...
;                 const int row = row0 + ai * 128 + m * 16; const float rs = rt[ai * 128 + wr * 64 + m * 16 + fr];
; #pragma unroll
;                 for (int bj = 0; bj < 2; ++bj) {
;                     const int cb = bj * 128 + wc * 32 + 8 * fq;
;                     const u32x4 w = pack8(acc[ai][bj][m][0] * rs, acc[ai][bj][m][1] * rs);
;                     bf16_t* dst;
;                     if (u.pn < 2) dst = Q + (size_t)row * 512 + u.pn * 256 + cb;
;                     else if (u.pn == 2) dst = (bj == 0 ? K : V) + (size_t)row * 128 + wc * 32 + 8 * fq;
;                     else { const int j = (u.pn - 3) * 256 + cb, g = j >> 4, h = j & 15; dst = UB + ((size_t)(g * NCH + (row >> 5)) * UK + (row & 31) * 16 + h); }
;                     *(u32x4*)dst = w;
.LBB0_215:
	s_waitcnt lgkmcnt(0)
	v_pk_mul_f32 v[94:95], v[94:95], v[96:97] op_sel_hi:[1,0]
	v_pk_mul_f32 v[92:93], v[92:93], v[96:97] op_sel_hi:[1,0]
	v_pk_mul_f32 v[104:105], v[90:91], v[96:97] op_sel_hi:[1,0]
	v_pk_mul_f32 v[90:91], v[88:89], v[96:97] op_sel_hi:[1,0]
	v_cvt_pk_bf16_f32 v88, v92, v93
	v_cvt_pk_bf16_f32 v89, v94, v95
	v_cvt_pk_bf16_f32 v90, v90, v91
	v_cvt_pk_bf16_f32 v91, v104, v105
	s_and_b64 vcc, exec, s[42:43]
	s_mov_b64 s[28:29], -1
	flat_store_dwordx4 v[102:103], v[88:91] sc1
	s_cbranch_vccnz .LBB0_221
	s_and_b64 vcc, exec, s[40:41]
	s_cbranch_vccnz .LBB0_218
	v_or_b32_e32 v88, s11, v160
	v_lshlrev_b32_e32 v88, 5, v88
	v_and_b32_e32 v88, 0x7ffffe00, v88
	v_add_u32_e32 v88, v97, v88
	v_mad_i64_i32 v[88:89], s[28:29], v88, s60, v[140:141]
	s_mov_b64 s[28:29], 0

; __device__ __forceinline__ u32x4 pack8(f32x4 v0, f32x4 v1) { u32x4 w; w.x = pk2(v0[0], v0[1]); w.y = pk2(v0[2], v0[3]); w.z = pk2(v1[0], v1[1]); w.w = pk2(v1[2], v1[3]); return w; }
;     __device__ __forceinline__ void operator()(const f32x4 (&acc)[2][2][4][2], const Unit& u, int wr, int wc, int fr, int fq) const {
;     ...
;                 const int row = row0 + ai * 128 + m * 16; const float rs = rt[ai * 128 + wr * 64 + m * 16 + fr];
; #pragma unroll
;                 for (int bj = 0; bj < 2; ++bj) {
;                     const int cb = bj * 128 + wc * 32 + 8 * fq;
;                     const u32x4 w = pack8(acc[ai][bj][m][0] * rs, acc[ai][bj][m][1] * rs);
;                     bf16_t* dst;
;                     if (u.pn < 2) dst = Q + (size_t)row * 512 + u.pn * 256 + cb;
;                     else if (u.pn == 2) dst = (bj == 0 ? K : V) + (size_t)row * 128 + wc * 32 + 8 * fq;
;                     else { const int j = (u.pn - 3) * 256 + cb, g = j >> 4, h = j & 15; dst = UB + ((size_t)(g * NCH + (row >> 5)) * UK + (row & 31) * 16 + h); }
;                     *(u32x4*)dst = w;
.LBB0_223:
	v_mov_b32_e32 v97, v96
	v_mov_b32_e32 v90, v96
	v_mov_b32_e32 v91, v96
	v_pk_mul_f32 v[86:87], v[86:87], v[90:91]
	v_pk_mul_f32 v[84:85], v[84:85], v[96:97]
	v_pk_mul_f32 v[90:91], v[82:83], v[90:91]
	v_pk_mul_f32 v[82:83], v[80:81], v[96:97]
	v_cvt_pk_bf16_f32 v80, v84, v85
	v_cvt_pk_bf16_f32 v81, v86, v87
	v_cvt_pk_bf16_f32 v82, v82, v83
	v_cvt_pk_bf16_f32 v83, v90, v91
	flat_store_dwordx4 v[88:89], v[80:83] sc1
	ds_read_b32 v80, v163 offset:192
	v_or_b32_e32 v84, 48, v150
	v_lshlrev_b32_e32 v81, 4, v84
	v_ashrrev_i32_e32 v85, 31, v84
	v_ashrrev_i32_e32 v88, 5, v84
	v_and_b32_e32 v81, 0x1f0, v81
	v_lshlrev_b64 v[82:83], 8, v[84:85]
	s_and_b64 vcc, exec, s[42:43]
	s_mov_b64 s[28:29], -1
	s_cbranch_vccnz .LBB0_229
	s_and_b64 vcc, exec, s[40:41]
	s_cbranch_vccnz .LBB0_226
	v_or_b32_e32 v86, s11, v138
	v_lshlrev_b32_e32 v86, 5, v86
	v_and_b32_e32 v86, 0x7fffee00, v86
	v_add_u32_e32 v89, v88, v86
	v_mov_b64_e32 v[86:87], s[44:45]
	v_mad_i64_i32 v[86:87], s[28:29], v89, s60, v[86:87]
	v_lshlrev_b32_e32 v90, 1, v81
	v_mov_b32_e32 v91, v201
	v_lshl_add_u64 v[86:87], v[86:87], 0, v[90:91]
	v_lshlrev_b32_e32 v90, 1, v136
	v_lshl_add_u64 v[86:87], v[86:87], 0, v[90:91]
	s_mov_b64 s[28:29], 0

; __device__ __forceinline__ u32x4 pack8(f32x4 v0, f32x4 v1) { u32x4 w; w.x = pk2(v0[0], v0[1]); w.y = pk2(v0[2], v0[3]); w.z = pk2(v1[0], v1[1]); w.w = pk2(v1[2], v1[3]); return w; }
;     __device__ __forceinline__ void operator()(const f32x4 (&acc)[2][2][4][2], const Unit& u, int wr, int wc, int fr, int fq) const {
;     ...
;                 const int row = row0 + ai * 128 + m * 16; const float rs = rt[ai * 128 + wr * 64 + m * 16 + fr];
; #pragma unroll
;                 for (int bj = 0; bj < 2; ++bj) {
;                     const int cb = bj * 128 + wc * 32 + 8 * fq;
;                     const u32x4 w = pack8(acc[ai][bj][m][0] * rs, acc[ai][bj][m][1] * rs);
;                     bf16_t* dst;
;                     if (u.pn < 2) dst = Q + (size_t)row * 512 + u.pn * 256 + cb;
;                     else if (u.pn == 2) dst = (bj == 0 ? K : V) + (size_t)row * 128 + wc * 32 + 8 * fq;
;                     else { const int j = (u.pn - 3) * 256 + cb, g = j >> 4, h = j & 15; dst = UB + ((size_t)(g * NCH + (row >> 5)) * UK + (row & 31) * 16 + h); }
;                     *(u32x4*)dst = w;
.LBB0_231:
	s_waitcnt lgkmcnt(0)
	v_pk_mul_f32 v[78:79], v[78:79], v[80:81] op_sel_hi:[1,0]
	v_pk_mul_f32 v[76:77], v[76:77], v[80:81] op_sel_hi:[1,0]
	v_pk_mul_f32 v[90:91], v[74:75], v[80:81] op_sel_hi:[1,0]
	v_pk_mul_f32 v[74:75], v[72:73], v[80:81] op_sel_hi:[1,0]
	v_cvt_pk_bf16_f32 v72, v76, v77
	v_cvt_pk_bf16_f32 v73, v78, v79
	v_cvt_pk_bf16_f32 v74, v74, v75
	v_cvt_pk_bf16_f32 v75, v90, v91
	s_and_b64 vcc, exec, s[42:43]
	s_mov_b64 s[28:29], -1
	flat_store_dwordx4 v[86:87], v[72:75] sc1
	s_cbranch_vccnz .LBB0_237
	s_and_b64 vcc, exec, s[40:41]
	s_cbranch_vccnz .LBB0_234
	v_or_b32_e32 v72, s11, v160
	v_lshlrev_b32_e32 v72, 5, v72
	v_and_b32_e32 v72, 0x7ffffe00, v72
	v_add_u32_e32 v74, v88, v72
	v_mov_b64_e32 v[72:73], s[44:45]
	v_mad_i64_i32 v[72:73], s[28:29], v74, s60, v[72:73]
	v_lshlrev_b32_e32 v74, 1, v81
	v_mov_b32_e32 v75, v201
	v_lshl_add_u64 v[72:73], v[72:73], 0, v[74:75]
	v_lshlrev_b32_e32 v74, 1, v136
	v_lshl_add_u64 v[72:73], v[72:73], 0, v[74:75]
	s_mov_b64 s[28:29], 0

; __device__ __forceinline__ u32x4 pack8(f32x4 v0, f32x4 v1) { u32x4 w; w.x = pk2(v0[0], v0[1]); w.y = pk2(v0[2], v0[3]); w.z = pk2(v1[0], v1[1]); w.w = pk2(v1[2], v1[3]); return w; }
;     __device__ __forceinline__ void operator()(const f32x4 (&acc)[2][2][4][2], const Unit& u, int wr, int wc, int fr, int fq) const {
;     ...
;                 const int row = row0 + ai * 128 + m * 16; const float rs = rt[ai * 128 + wr * 64 + m * 16 + fr];
; #pragma unroll
;                 for (int bj = 0; bj < 2; ++bj) {
;                     const int cb = bj * 128 + wc * 32 + 8 * fq;
;                     const u32x4 w = pack8(acc[ai][bj][m][0] * rs, acc[ai][bj][m][1] * rs);
;                     bf16_t* dst;
;                     if (u.pn < 2) dst = Q + (size_t)row * 512 + u.pn * 256 + cb;
;                     else if (u.pn == 2) dst = (bj == 0 ? K : V) + (size_t)row * 128 + wc * 32 + 8 * fq;
;                     else { const int j = (u.pn - 3) * 256 + cb, g = j >> 4, h = j & 15; dst = UB + ((size_t)(g * NCH + (row >> 5)) * UK + (row & 31) * 16 + h); }
;                     *(u32x4*)dst = w;
.LBB0_239:
	v_mov_b32_e32 v81, v80
	v_mov_b32_e32 v74, v80
	v_mov_b32_e32 v75, v80
	v_pk_mul_f32 v[70:71], v[70:71], v[74:75]
	v_pk_mul_f32 v[68:69], v[68:69], v[80:81]
	v_pk_mul_f32 v[74:75], v[66:67], v[74:75]
	v_pk_mul_f32 v[66:67], v[64:65], v[80:81]
	v_cvt_pk_bf16_f32 v64, v68, v69
	v_cvt_pk_bf16_f32 v65, v70, v71
	v_cvt_pk_bf16_f32 v66, v66, v67
	v_cvt_pk_bf16_f32 v67, v74, v75
	flat_store_dwordx4 v[72:73], v[64:67] sc1
	ds_read_b32 v64, v163 offset:512
	v_add_u32_e32 v68, 0x80, v150
	v_ashrrev_i32_e32 v69, 31, v68
	v_ashrrev_i32_e32 v65, 5, v68
	v_lshlrev_b64 v[66:67], 8, v[68:69]
	s_and_b64 vcc, exec, s[42:43]
	s_mov_b64 s[28:29], -1
	s_cbranch_vccnz .LBB0_245
	s_and_b64 vcc, exec, s[40:41]
	s_cbranch_vccnz .LBB0_242
	v_or_b32_e32 v70, s11, v138
	v_lshlrev_b32_e32 v70, 5, v70
	v_and_b32_e32 v70, 0x7fffee00, v70
	v_add_u32_e32 v70, v65, v70
	v_mad_i64_i32 v[70:71], s[28:29], v70, s60, v[140:141]
	s_mov_b64 s[28:29], 0

; __device__ __forceinline__ u32x4 pack8(f32x4 v0, f32x4 v1) { u32x4 w; w.x = pk2(v0[0], v0[1]); w.y = pk2(v0[2], v0[3]); w.z = pk2(v1[0], v1[1]); w.w = pk2(v1[2], v1[3]); return w; }
;     __device__ __forceinline__ void operator()(const f32x4 (&acc)[2][2][4][2], const Unit& u, int wr, int wc, int fr, int fq) const {
;     ...
;                 const int row = row0 + ai * 128 + m * 16; const float rs = rt[ai * 128 + wr * 64 + m * 16 + fr];
; #pragma unroll
;                 for (int bj = 0; bj < 2; ++bj) {
;                     const int cb = bj * 128 + wc * 32 + 8 * fq;
;                     const u32x4 w = pack8(acc[ai][bj][m][0] * rs, acc[ai][bj][m][1] * rs);
;                     bf16_t* dst;
;                     if (u.pn < 2) dst = Q + (size_t)row * 512 + u.pn * 256 + cb;
;                     else if (u.pn == 2) dst = (bj == 0 ? K : V) + (size_t)row * 128 + wc * 32 + 8 * fq;
;                     else { const int j = (u.pn - 3) * 256 + cb, g = j >> 4, h = j & 15; dst = UB + ((size_t)(g * NCH + (row >> 5)) * UK + (row & 31) * 16 + h); }
;                     *(u32x4*)dst = w;
.LBB0_247:
	s_waitcnt lgkmcnt(0)
	v_pk_mul_f32 v[62:63], v[62:63], v[64:65] op_sel_hi:[1,0]
	v_pk_mul_f32 v[60:61], v[60:61], v[64:65] op_sel_hi:[1,0]
	v_pk_mul_f32 v[72:73], v[58:59], v[64:65] op_sel_hi:[1,0]
	v_pk_mul_f32 v[58:59], v[56:57], v[64:65] op_sel_hi:[1,0]
	v_cvt_pk_bf16_f32 v56, v60, v61
	v_cvt_pk_bf16_f32 v57, v62, v63
	v_cvt_pk_bf16_f32 v58, v58, v59
	v_cvt_pk_bf16_f32 v59, v72, v73
	s_and_b64 vcc, exec, s[42:43]
	s_mov_b64 s[28:29], -1
	flat_store_dwordx4 v[70:71], v[56:59] sc1
	s_cbranch_vccnz .LBB0_253
	s_and_b64 vcc, exec, s[40:41]
	s_cbranch_vccnz .LBB0_250
	v_or_b32_e32 v56, s11, v160
	v_lshlrev_b32_e32 v56, 5, v56
	v_and_b32_e32 v56, 0x7ffffe00, v56
	v_add_u32_e32 v56, v65, v56
	v_mad_i64_i32 v[56:57], s[28:29], v56, s60, v[140:141]
	s_mov_b64 s[28:29], 0

; __device__ __forceinline__ u32x4 pack8(f32x4 v0, f32x4 v1) { u32x4 w; w.x = pk2(v0[0], v0[1]); w.y = pk2(v0[2], v0[3]); w.z = pk2(v1[0], v1[1]); w.w = pk2(v1[2], v1[3]); return w; }
;     __device__ __forceinline__ void operator()(const f32x4 (&acc)[2][2][4][2], const Unit& u, int wr, int wc, int fr, int fq) const {
;     ...
;                 const int row = row0 + ai * 128 + m * 16; const float rs = rt[ai * 128 + wr * 64 + m * 16 + fr];
; #pragma unroll
;                 for (int bj = 0; bj < 2; ++bj) {
;                     const int cb = bj * 128 + wc * 32 + 8 * fq;
;                     const u32x4 w = pack8(acc[ai][bj][m][0] * rs, acc[ai][bj][m][1] * rs);
;                     bf16_t* dst;
;                     if (u.pn < 2) dst = Q + (size_t)row * 512 + u.pn * 256 + cb;
;                     else if (u.pn == 2) dst = (bj == 0 ? K : V) + (size_t)row * 128 + wc * 32 + 8 * fq;
;                     else { const int j = (u.pn - 3) * 256 + cb, g = j >> 4, h = j & 15; dst = UB + ((size_t)(g * NCH + (row >> 5)) * UK + (row & 31) * 16 + h); }
;                     *(u32x4*)dst = w;
.LBB0_255:
	v_mov_b32_e32 v65, v64
	v_mov_b32_e32 v58, v64
	v_mov_b32_e32 v59, v64
	v_pk_mul_f32 v[54:55], v[54:55], v[58:59]
	v_pk_mul_f32 v[52:53], v[52:53], v[64:65]
	v_pk_mul_f32 v[58:59], v[50:51], v[58:59]
	v_pk_mul_f32 v[50:51], v[48:49], v[64:65]
	v_cvt_pk_bf16_f32 v48, v52, v53
	v_cvt_pk_bf16_f32 v49, v54, v55
	v_cvt_pk_bf16_f32 v50, v50, v51
	v_cvt_pk_bf16_f32 v51, v58, v59
	flat_store_dwordx4 v[56:57], v[48:51] sc1
	ds_read_b32 v48, v163 offset:576
	v_add_u32_e32 v52, 0x90, v150
	v_lshlrev_b32_e32 v49, 4, v52
	v_ashrrev_i32_e32 v53, 31, v52
	v_ashrrev_i32_e32 v56, 5, v52
	v_and_b32_e32 v49, 0x1f0, v49
	v_lshlrev_b64 v[50:51], 8, v[52:53]
	s_and_b64 vcc, exec, s[42:43]
	s_mov_b64 s[28:29], -1
	s_cbranch_vccnz .LBB0_261
	s_and_b64 vcc, exec, s[40:41]
	s_cbranch_vccnz .LBB0_258
	v_or_b32_e32 v54, s11, v138
	v_lshlrev_b32_e32 v54, 5, v54
	v_and_b32_e32 v54, 0x7fffee00, v54
	v_add_u32_e32 v57, v56, v54
	v_mov_b64_e32 v[54:55], s[44:45]
	v_mad_i64_i32 v[54:55], s[28:29], v57, s60, v[54:55]
	v_lshlrev_b32_e32 v58, 1, v49
	v_mov_b32_e32 v59, v201
	v_lshl_add_u64 v[54:55], v[54:55], 0, v[58:59]
	v_lshlrev_b32_e32 v58, 1, v136
	v_lshl_add_u64 v[54:55], v[54:55], 0, v[58:59]
	s_mov_b64 s[28:29], 0

; __device__ __forceinline__ u32x4 pack8(f32x4 v0, f32x4 v1) { u32x4 w; w.x = pk2(v0[0], v0[1]); w.y = pk2(v0[2], v0[3]); w.z = pk2(v1[0], v1[1]); w.w = pk2(v1[2], v1[3]); return w; }
;     __device__ __forceinline__ void operator()(const f32x4 (&acc)[2][2][4][2], const Unit& u, int wr, int wc, int fr, int fq) const {
;     ...
;                 const int row = row0 + ai * 128 + m * 16; const float rs = rt[ai * 128 + wr * 64 + m * 16 + fr];
; #pragma unroll
;                 for (int bj = 0; bj < 2; ++bj) {
;                     const int cb = bj * 128 + wc * 32 + 8 * fq;
;                     const u32x4 w = pack8(acc[ai][bj][m][0] * rs, acc[ai][bj][m][1] * rs);
;                     bf16_t* dst;
;                     if (u.pn < 2) dst = Q + (size_t)row * 512 + u.pn * 256 + cb;
;                     else if (u.pn == 2) dst = (bj == 0 ? K : V) + (size_t)row * 128 + wc * 32 + 8 * fq;
;                     else { const int j = (u.pn - 3) * 256 + cb, g = j >> 4, h = j & 15; dst = UB + ((size_t)(g * NCH + (row >> 5)) * UK + (row & 31) * 16 + h); }
;                     *(u32x4*)dst = w;
.LBB0_263:
	s_waitcnt lgkmcnt(0)
	v_pk_mul_f32 v[46:47], v[46:47], v[48:49] op_sel_hi:[1,0]
	v_pk_mul_f32 v[44:45], v[44:45], v[48:49] op_sel_hi:[1,0]
	v_pk_mul_f32 v[58:59], v[42:43], v[48:49] op_sel_hi:[1,0]
	v_pk_mul_f32 v[42:43], v[40:41], v[48:49] op_sel_hi:[1,0]
	v_cvt_pk_bf16_f32 v40, v44, v45
	v_cvt_pk_bf16_f32 v41, v46, v47
	v_cvt_pk_bf16_f32 v42, v42, v43
	v_cvt_pk_bf16_f32 v43, v58, v59
	s_and_b64 vcc, exec, s[42:43]
	s_mov_b64 s[28:29], -1
	flat_store_dwordx4 v[54:55], v[40:43] sc1
	s_cbranch_vccnz .LBB0_269
	s_and_b64 vcc, exec, s[40:41]
	s_cbranch_vccnz .LBB0_266
	v_or_b32_e32 v40, s11, v160
	v_lshlrev_b32_e32 v40, 5, v40
	v_and_b32_e32 v40, 0x7ffffe00, v40
	v_add_u32_e32 v42, v56, v40
	v_mov_b64_e32 v[40:41], s[44:45]
	v_mad_i64_i32 v[40:41], s[28:29], v42, s60, v[40:41]
	v_lshlrev_b32_e32 v42, 1, v49
	v_mov_b32_e32 v43, v201
	v_lshl_add_u64 v[40:41], v[40:41], 0, v[42:43]
	v_lshlrev_b32_e32 v42, 1, v136
	v_lshl_add_u64 v[40:41], v[40:41], 0, v[42:43]
	s_mov_b64 s[28:29], 0

; __device__ __forceinline__ u32x4 pack8(f32x4 v0, f32x4 v1) { u32x4 w; w.x = pk2(v0[0], v0[1]); w.y = pk2(v0[2], v0[3]); w.z = pk2(v1[0], v1[1]); w.w = pk2(v1[2], v1[3]); return w; }
;     __device__ __forceinline__ void operator()(const f32x4 (&acc)[2][2][4][2], const Unit& u, int wr, int wc, int fr, int fq) const {
;     ...
;                 const int row = row0 + ai * 128 + m * 16; const float rs = rt[ai * 128 + wr * 64 + m * 16 + fr];
; #pragma unroll
;                 for (int bj = 0; bj < 2; ++bj) {
;                     const int cb = bj * 128 + wc * 32 + 8 * fq;
;                     const u32x4 w = pack8(acc[ai][bj][m][0] * rs, acc[ai][bj][m][1] * rs);
;                     bf16_t* dst;
;                     if (u.pn < 2) dst = Q + (size_t)row * 512 + u.pn * 256 + cb;
;                     else if (u.pn == 2) dst = (bj == 0 ? K : V) + (size_t)row * 128 + wc * 32 + 8 * fq;
;                     else { const int j = (u.pn - 3) * 256 + cb, g = j >> 4, h = j & 15; dst = UB + ((size_t)(g * NCH + (row >> 5)) * UK + (row & 31) * 16 + h); }
;                     *(u32x4*)dst = w;
.LBB0_271:
	v_mov_b32_e32 v49, v48
	v_mov_b32_e32 v42, v48
	v_mov_b32_e32 v43, v48
	v_pk_mul_f32 v[38:39], v[38:39], v[42:43]
	v_pk_mul_f32 v[36:37], v[36:37], v[48:49]
	v_pk_mul_f32 v[42:43], v[34:35], v[42:43]
	v_pk_mul_f32 v[34:35], v[32:33], v[48:49]
	v_cvt_pk_bf16_f32 v32, v36, v37
	v_cvt_pk_bf16_f32 v33, v38, v39
	v_cvt_pk_bf16_f32 v34, v34, v35
	v_cvt_pk_bf16_f32 v35, v42, v43
	flat_store_dwordx4 v[40:41], v[32:35] sc1
	ds_read_b32 v32, v163 offset:640
	v_add_u32_e32 v36, 0xa0, v150
	v_ashrrev_i32_e32 v37, 31, v36
	v_ashrrev_i32_e32 v33, 5, v36
	v_lshlrev_b64 v[34:35], 8, v[36:37]
	s_and_b64 vcc, exec, s[42:43]
	s_mov_b64 s[28:29], -1
	s_cbranch_vccnz .LBB0_277
	s_and_b64 vcc, exec, s[40:41]
	s_cbranch_vccnz .LBB0_274
	v_or_b32_e32 v38, s11, v138
	v_lshlrev_b32_e32 v38, 5, v38
	v_and_b32_e32 v38, 0x7fffee00, v38
	v_add_u32_e32 v38, v33, v38
	v_mad_i64_i32 v[38:39], s[28:29], v38, s60, v[140:141]
	s_mov_b64 s[28:29], 0

; __device__ __forceinline__ u32x4 pack8(f32x4 v0, f32x4 v1) { u32x4 w; w.x = pk2(v0[0], v0[1]); w.y = pk2(v0[2], v0[3]); w.z = pk2(v1[0], v1[1]); w.w = pk2(v1[2], v1[3]); return w; }
;     __device__ __forceinline__ void operator()(const f32x4 (&acc)[2][2][4][2], const Unit& u, int wr, int wc, int fr, int fq) const {
;     ...
;                 const int row = row0 + ai * 128 + m * 16; const float rs = rt[ai * 128 + wr * 64 + m * 16 + fr];
; #pragma unroll
;                 for (int bj = 0; bj < 2; ++bj) {
;                     const int cb = bj * 128 + wc * 32 + 8 * fq;
;                     const u32x4 w = pack8(acc[ai][bj][m][0] * rs, acc[ai][bj][m][1] * rs);
;                     bf16_t* dst;
;                     if (u.pn < 2) dst = Q + (size_t)row * 512 + u.pn * 256 + cb;
;                     else if (u.pn == 2) dst = (bj == 0 ? K : V) + (size_t)row * 128 + wc * 32 + 8 * fq;
;                     else { const int j = (u.pn - 3) * 256 + cb, g = j >> 4, h = j & 15; dst = UB + ((size_t)(g * NCH + (row >> 5)) * UK + (row & 31) * 16 + h); }
;                     *(u32x4*)dst = w;
.LBB0_279:
	s_waitcnt lgkmcnt(0)
	v_pk_mul_f32 v[30:31], v[30:31], v[32:33] op_sel_hi:[1,0]
	v_pk_mul_f32 v[28:29], v[28:29], v[32:33] op_sel_hi:[1,0]
	v_pk_mul_f32 v[40:41], v[26:27], v[32:33] op_sel_hi:[1,0]
	v_pk_mul_f32 v[26:27], v[24:25], v[32:33] op_sel_hi:[1,0]
	v_cvt_pk_bf16_f32 v24, v28, v29
	v_cvt_pk_bf16_f32 v25, v30, v31
	v_cvt_pk_bf16_f32 v26, v26, v27
	v_cvt_pk_bf16_f32 v27, v40, v41
	s_and_b64 vcc, exec, s[42:43]
	s_mov_b64 s[28:29], -1
	flat_store_dwordx4 v[38:39], v[24:27] sc1
	s_cbranch_vccnz .LBB0_285
	s_and_b64 vcc, exec, s[40:41]
	s_cbranch_vccnz .LBB0_282
	v_or_b32_e32 v24, s11, v160
	v_lshlrev_b32_e32 v24, 5, v24
	v_and_b32_e32 v24, 0x7ffffe00, v24
	v_add_u32_e32 v24, v33, v24
	v_mad_i64_i32 v[24:25], s[28:29], v24, s60, v[140:141]
	s_mov_b64 s[28:29], 0

; __device__ __forceinline__ u32x4 pack8(f32x4 v0, f32x4 v1) { u32x4 w; w.x = pk2(v0[0], v0[1]); w.y = pk2(v0[2], v0[3]); w.z = pk2(v1[0], v1[1]); w.w = pk2(v1[2], v1[3]); return w; }
;     __device__ __forceinline__ void operator()(const f32x4 (&acc)[2][2][4][2], const Unit& u, int wr, int wc, int fr, int fq) const {
;     ...
;                 const int row = row0 + ai * 128 + m * 16; const float rs = rt[ai * 128 + wr * 64 + m * 16 + fr];
; #pragma unroll
;                 for (int bj = 0; bj < 2; ++bj) {
;                     const int cb = bj * 128 + wc * 32 + 8 * fq;
;                     const u32x4 w = pack8(acc[ai][bj][m][0] * rs, acc[ai][bj][m][1] * rs);
;                     bf16_t* dst;
;                     if (u.pn < 2) dst = Q + (size_t)row * 512 + u.pn * 256 + cb;
;                     else if (u.pn == 2) dst = (bj == 0 ? K : V) + (size_t)row * 128 + wc * 32 + 8 * fq;
;                     else { const int j = (u.pn - 3) * 256 + cb, g = j >> 4, h = j & 15; dst = UB + ((size_t)(g * NCH + (row >> 5)) * UK + (row & 31) * 16 + h); }
;                     *(u32x4*)dst = w;
.LBB0_287:
	v_mov_b32_e32 v33, v32
	v_mov_b32_e32 v26, v32
	v_mov_b32_e32 v27, v32
	v_pk_mul_f32 v[22:23], v[22:23], v[26:27]
	v_pk_mul_f32 v[20:21], v[20:21], v[32:33]
	v_pk_mul_f32 v[26:27], v[18:19], v[26:27]
	v_pk_mul_f32 v[18:19], v[16:17], v[32:33]
	v_cvt_pk_bf16_f32 v16, v20, v21
	v_cvt_pk_bf16_f32 v17, v22, v23
	v_cvt_pk_bf16_f32 v18, v18, v19
	v_cvt_pk_bf16_f32 v19, v26, v27
	flat_store_dwordx4 v[24:25], v[16:19] sc1
	ds_read_b32 v16, v163 offset:704
	v_add_u32_e32 v20, 0xb0, v150
	v_lshlrev_b32_e32 v17, 4, v20
	v_ashrrev_i32_e32 v21, 31, v20
	v_ashrrev_i32_e32 v24, 5, v20
	v_and_b32_e32 v17, 0x1f0, v17
	v_lshlrev_b64 v[18:19], 8, v[20:21]
	s_and_b64 vcc, exec, s[42:43]
	s_mov_b64 s[28:29], -1
	s_cbranch_vccnz .LBB0_293
	s_and_b64 vcc, exec, s[40:41]
	s_cbranch_vccnz .LBB0_290
	v_or_b32_e32 v22, s11, v138
	v_lshlrev_b32_e32 v22, 5, v22
	v_and_b32_e32 v22, 0x7fffee00, v22
	v_add_u32_e32 v25, v24, v22
	v_mov_b64_e32 v[22:23], s[44:45]
	v_mad_i64_i32 v[22:23], s[28:29], v25, s60, v[22:23]
	v_lshlrev_b32_e32 v26, 1, v17
	v_mov_b32_e32 v27, v201
	v_lshl_add_u64 v[22:23], v[22:23], 0, v[26:27]
	v_lshlrev_b32_e32 v26, 1, v136
	v_lshl_add_u64 v[22:23], v[22:23], 0, v[26:27]
	s_mov_b64 s[28:29], 0

; __device__ __forceinline__ u32x4 pack8(f32x4 v0, f32x4 v1) { u32x4 w; w.x = pk2(v0[0], v0[1]); w.y = pk2(v0[2], v0[3]); w.z = pk2(v1[0], v1[1]); w.w = pk2(v1[2], v1[3]); return w; }
;     __device__ __forceinline__ void operator()(const f32x4 (&acc)[2][2][4][2], const Unit& u, int wr, int wc, int fr, int fq) const {
;     ...
;                 const int row = row0 + ai * 128 + m * 16; const float rs = rt[ai * 128 + wr * 64 + m * 16 + fr];
; #pragma unroll
;                 for (int bj = 0; bj < 2; ++bj) {
;                     const int cb = bj * 128 + wc * 32 + 8 * fq;
;                     const u32x4 w = pack8(acc[ai][bj][m][0] * rs, acc[ai][bj][m][1] * rs);
;                     bf16_t* dst;
;                     if (u.pn < 2) dst = Q + (size_t)row * 512 + u.pn * 256 + cb;
;                     else if (u.pn == 2) dst = (bj == 0 ? K : V) + (size_t)row * 128 + wc * 32 + 8 * fq;
;                     else { const int j = (u.pn - 3) * 256 + cb, g = j >> 4, h = j & 15; dst = UB + ((size_t)(g * NCH + (row >> 5)) * UK + (row & 31) * 16 + h); }
;                     *(u32x4*)dst = w;
.LBB0_295:
	s_waitcnt lgkmcnt(0)
	v_pk_mul_f32 v[14:15], v[14:15], v[16:17] op_sel_hi:[1,0]
	v_pk_mul_f32 v[12:13], v[12:13], v[16:17] op_sel_hi:[1,0]
	v_pk_mul_f32 v[26:27], v[10:11], v[16:17] op_sel_hi:[1,0]
	v_pk_mul_f32 v[10:11], v[8:9], v[16:17] op_sel_hi:[1,0]
	v_cvt_pk_bf16_f32 v8, v12, v13
	v_cvt_pk_bf16_f32 v9, v14, v15
	v_cvt_pk_bf16_f32 v10, v10, v11
	v_cvt_pk_bf16_f32 v11, v26, v27
	s_and_b64 vcc, exec, s[42:43]
	s_mov_b64 s[22:23], -1
	flat_store_dwordx4 v[22:23], v[8:11] sc1
	s_cbranch_vccnz .LBB0_301
	s_and_b64 vcc, exec, s[40:41]
	s_cbranch_vccnz .LBB0_298
	v_or_b32_e32 v8, s11, v160
	v_lshlrev_b32_e32 v8, 5, v8
	v_and_b32_e32 v8, 0x7ffffe00, v8
	v_add_u32_e32 v10, v24, v8
	v_mov_b64_e32 v[8:9], s[44:45]
	v_mad_i64_i32 v[8:9], s[22:23], v10, s60, v[8:9]
	v_lshlrev_b32_e32 v10, 1, v17
	v_mov_b32_e32 v11, v201
	v_lshl_add_u64 v[8:9], v[8:9], 0, v[10:11]
	v_lshlrev_b32_e32 v10, 1, v136
	v_lshl_add_u64 v[8:9], v[8:9], 0, v[10:11]
	s_mov_b64 s[22:23], 0

; __device__ __forceinline__ u32x4 pack8(f32x4 v0, f32x4 v1) { u32x4 w; w.x = pk2(v0[0], v0[1]); w.y = pk2(v0[2], v0[3]); w.z = pk2(v1[0], v1[1]); w.w = pk2(v1[2], v1[3]); return w; }
;     __device__ __forceinline__ void operator()(const f32x4 (&acc)[2][2][4][2], const Unit& u, int wr, int wc, int fr, int fq) const {
;     ...
;                 const int row = row0 + ai * 128 + m * 16; const float rs = rt[ai * 128 + wr * 64 + m * 16 + fr];
; #pragma unroll
;                 for (int bj = 0; bj < 2; ++bj) {
;                     const int cb = bj * 128 + wc * 32 + 8 * fq;
;                     const u32x4 w = pack8(acc[ai][bj][m][0] * rs, acc[ai][bj][m][1] * rs);
;                     bf16_t* dst;
;                     if (u.pn < 2) dst = Q + (size_t)row * 512 + u.pn * 256 + cb;
;                     else if (u.pn == 2) dst = (bj == 0 ? K : V) + (size_t)row * 128 + wc * 32 + 8 * fq;
;                     else { const int j = (u.pn - 3) * 256 + cb, g = j >> 4, h = j & 15; dst = UB + ((size_t)(g * NCH + (row >> 5)) * UK + (row & 31) * 16 + h); }
;                     *(u32x4*)dst = w;
.LBB0_303:
	v_mov_b32_e32 v17, v16
	v_mov_b32_e32 v10, v16
	v_mov_b32_e32 v11, v16
	v_pk_mul_f32 v[6:7], v[6:7], v[10:11]
	v_pk_mul_f32 v[4:5], v[4:5], v[16:17]
	v_pk_mul_f32 v[2:3], v[2:3], v[10:11]
	v_pk_mul_f32 v[0:1], v[0:1], v[16:17]
	v_cvt_pk_bf16_f32 v4, v4, v5
	v_cvt_pk_bf16_f32 v5, v6, v7
	v_cvt_pk_bf16_f32 v6, v0, v1
	v_cvt_pk_bf16_f32 v7, v2, v3
	s_andn2_b64 vcc, exec, s[38:39]
	s_mov_b64 s[22:23], -1
	flat_store_dwordx4 v[8:9], v[4:7] sc1
	s_cbranch_vccnz .LBB0_168
	s_andn2_b64 vcc, exec, s[4:5]
	s_cbranch_vccnz .LBB0_167
	s_barrier
	s_branch .LBB0_167
